# phase 0: the 96 modulation workgroups take a share of the w_in transposes after their GEMV item (virtual blk 160+b, all workgroups stride 256 tiles)
# speedup vs baseline: 1.0173x; 1.0008x over previous
.LBB0_144:
	s_cmp_eq_u32 s34, 0x100
	s_cselect_b32 s69, 0x100, s69
	s_cmpk_gt_i32 s68, 0x37f
	s_cbranch_scc1 .LBB0_150
	s_ashr_i32 s0, s68, 31
	s_lshr_b32 s0, s0, 28
	s_add_i32 s0, s68, s0
	s_lshl_b32 s1, s0, 2
	s_movk_i32 s2, 0xffc0
	s_and_b32 s0, s0, 0x3fffff0
	v_mov_b32_e32 v0, s1
	s_sub_i32 s0, s68, s0
	v_bfi_b32 v0, s2, v0, v160
	v_lshlrev_b32_e32 v2, 6, v160
	s_lshl_b32 s0, s0, 6
	s_movk_i32 s4, 0x400
	s_and_b32 s2, s1, 0xffffff80
	v_bfe_u32 v1, v0, 1, 6
	v_and_b32_e32 v2, 64, v2
	v_lshrrev_b32_e32 v3, 6, v160
	v_or3_b32 v1, s2, v1, v2
	v_cmp_gt_i32_e32 vcc, s4, v0
	s_waitcnt vmcnt(7)
	v_or_b32_e32 v18, s0, v3
	s_movk_i32 s2, 0xe00
	v_cndmask_b32_e32 v0, v0, v1, vcc
	v_mul_lo_u32 v4, v18, s2
	v_ashrrev_i32_e32 v5, 31, v4
	v_ashrrev_i32_e32 v1, 31, v0
	v_lshl_add_u64 v[4:5], v[4:5], 2, s[52:53]
	v_lshlrev_b64 v[0:1], 2, v[0:1]
	v_lshl_add_u64 v[8:9], v[4:5], 0, v[0:1]
	v_add_u32_e32 v4, 0x200, v160
	v_lshrrev_b32_e32 v4, 6, v4
	v_or_b32_e32 v5, s0, v4
	v_mul_lo_u32 v6, v5, s2
	v_ashrrev_i32_e32 v7, 31, v6
	v_lshl_add_u64 v[6:7], v[6:7], 2, s[52:53]
	v_or_b32_e32 v5, 16, v18
	v_lshl_add_u64 v[10:11], v[6:7], 0, v[0:1]
	v_mul_lo_u32 v6, v5, s2
	v_ashrrev_i32_e32 v7, 31, v6
	v_add_u32_e32 v5, 0x600, v160
	v_lshl_add_u64 v[6:7], v[6:7], 2, s[52:53]
	v_lshrrev_b32_e32 v5, 6, v5
	v_lshl_add_u64 v[12:13], v[6:7], 0, v[0:1]
	v_or_b32_e32 v6, s0, v5
	v_mul_lo_u32 v6, v6, s2
	v_ashrrev_i32_e32 v7, 31, v6
	v_lshl_add_u64 v[6:7], v[6:7], 2, s[52:53]
	v_lshl_add_u64 v[14:15], v[6:7], 0, v[0:1]
	v_or_b32_e32 v6, 32, v18
	v_mul_lo_u32 v6, v6, s2
	v_ashrrev_i32_e32 v7, 31, v6
	v_lshl_add_u64 v[6:7], v[6:7], 2, s[52:53]
	s_waitcnt vmcnt(2)
	v_lshl_add_u64 v[22:23], v[6:7], 0, v[0:1]
	v_add_u32_e32 v6, 0xa00, v160
	v_lshrrev_b32_e32 v6, 6, v6
	v_or_b32_e32 v7, s0, v6
	v_mul_lo_u32 v16, v7, s2
	v_ashrrev_i32_e32 v17, 31, v16
	v_lshl_add_u64 v[16:17], v[16:17], 2, s[52:53]
	v_or_b32_e32 v7, 48, v18
	s_waitcnt vmcnt(1)
	v_lshl_add_u64 v[24:25], v[16:17], 0, v[0:1]
	v_mul_lo_u32 v16, v7, s2
	v_ashrrev_i32_e32 v17, 31, v16
	v_add_u32_e32 v7, 0xe00, v160
	v_lshl_add_u64 v[16:17], v[16:17], 2, s[52:53]
	v_lshrrev_b32_e32 v7, 6, v7
	v_lshl_add_u64 v[26:27], v[16:17], 0, v[0:1]
	v_add_u32_e32 v16, s0, v7
	v_mul_lo_u32 v16, v16, s2
	v_ashrrev_i32_e32 v17, 31, v16
	v_lshl_add_u64 v[16:17], v[16:17], 2, s[52:53]
	v_lshl_add_u64 v[0:1], v[16:17], 0, v[0:1]
	global_load_dword v17, v[8:9], off
	global_load_dword v18, v[10:11], off
	global_load_dword v19, v[12:13], off
	global_load_dword v20, v[14:15], off
	global_load_dword v21, v[22:23], off
	s_nop 0
	global_load_dword v22, v[24:25], off
	global_load_dword v23, v[26:27], off
	s_nop 0
	global_load_dword v24, v[0:1], off
	v_lshlrev_b32_e32 v0, 3, v160
	s_add_i32 s2, s69, s20
	s_andn2_b32 s1, s1, 63
	v_and_b32_e32 v8, 63, v160
	v_lshrrev_b32_e32 v10, 3, v160
	v_and_b32_e32 v0, 56, v0
	s_mul_i32 s5, s2, 0x38000
	v_mul_u32_u24_e32 v13, 0xe00, v6
	v_mul_u32_u24_e32 v14, 0xe00, v5
	v_mul_u32_u24_e32 v15, 0xe00, v4
	s_lshl_b32 s2, s2, 6
	v_mul_u32_u24_e32 v16, 0xe00, v7
	v_mul_u32_u24_e32 v9, 0x90, v8
	v_mul_u32_u24_e32 v11, 0x90, v10
	v_mov_b32_e32 v1, 0
	v_mul_u32_u24_e32 v12, 0xe00, v3
	s_mul_i32 s6, s69, 0x38000
	v_or_b32_e32 v13, 0xfeb00000, v13
	v_or_b32_e32 v14, 0xfeb00000, v14
	v_or_b32_e32 v15, 0xfeb00000, v15
	s_add_i32 s7, s2, 0xffffe800
	s_lshl_b32 s8, s69, 6
	v_or_b32_e32 v16, 0xfeb00000, v16
	s_mov_b32 s9, 0
	s_movk_i32 s10, 0x7fff
	v_lshlrev_b32_e32 v0, 1, v0
	s_mov_b32 s11, s1
	s_branch .LBB0_147

.LBB0_150:
	s_cmpk_gt_u32 s20, 0xff
	s_cselect_b32 s20, s101, s20
	s_mov_b64 s[0:1], 0

.LBB0_159:
	s_or_b64 exec, exec, s[0:1]
	s_barrier
	s_cmp_lg_u32 s34, 0x100
	s_cbranch_scc1 .LBB0_160
	s_mov_b32 s101, s20
	s_addk_i32 s20, 0x100
	s_add_i32 s68, s20, 0xffffffa0
	s_movk_i32 s69, 0x100
	s_branch .LBB0_144
